# a+b plus: P5 epilogue next-unit constants wait counted (vmcnt(16): does not wait for the 16 G stores)
# baseline (speedup 1.0000x reference)
; #define PG8_LAS __attribute__((address_space(3)))
;     __device__ __forceinline__ void operator()(f32x4 (&acc)[2][2][4][2], const Unit& u, const Unit& nxt, bool has_next, int ui, int wr, int wc, int fr, int fq) const {
;     ...
;         asm volatile("s_waitcnt lgkmcnt(0)" ::: "memory"); __builtin_amdgcn_s_barrier(); asm volatile("" ::: "memory");
; #pragma unroll
;         for (int n = 0; n < 2; ++n) {
;             f32x4 wg[3], wv[3];
; #pragma unroll
;             for (int k = 0; k < 3; ++k) { wg[k] = *(const PG8_LAS f32x4*)(tab + k * 128 + 4 * n); wv[k] = *(const PG8_LAS f32x4*)(tab + (4 + k) * 128 + 4 * n); }
;             const f32x4 bg = *(const PG8_LAS f32x4*)(tab + 3 * 128 + 4 * n), bv = *(const PG8_LAS f32x4*)(tab + 7 * 128 + 4 * n);
; #pragma unroll
;             for (int ai = 0; ai < 2; ++ai) { const int blk = 2 * ai + wr; const int pblk = blk > 0 ? blk - 1 : 0; const float hz = blk > 0 ? 1.0f : 0.0f;
;                 f32x4 q2[2], q3[2];
; #pragma unroll
;                 for (int bj = 0; bj < 2; ++bj) {
;                     const PG8_LAS f32x4* hp = (const PG8_LAS f32x4*)(halo + ((pblk * 4 + wc) * 4 + fq) * 32 + (bj * 8 + n * 4) * 2);
;                     const f32x4 ha = hp[0] * hz, hb = hp[1] * hz;
;                     q2[bj][0] = dpp_shr1(ha[0], acc[ai][bj][2][n][0]); q3[bj][0] = dpp_shr1(ha[1], acc[ai][bj][3][n][0]);
;                     q2[bj][1] = dpp_shr1(ha[2], acc[ai][bj][2][n][1]); q3[bj][1] = dpp_shr1(ha[3], acc[ai][bj][3][n][1]);
;                     q2[bj][2] = dpp_shr1(hb[0], acc[ai][bj][2][n][2]); q3[bj][2] = dpp_shr1(hb[1], acc[ai][bj][3][n][2]);
;                     q2[bj][3] = dpp_shr1(hb[2], acc[ai][bj][2][n][3]); q3[bj][3] = dpp_shr1(hb[3], acc[ai][bj][3][n][3]); }
; #pragma unroll
;                 for (int m = 0; m < 4; ++m) { const int row = row0 + ai * HALF + m;
;                     const f32x4 s1g = (m == 0) ? q3[0] : acc[ai][0][m > 0 ? m - 1 : 0][n], s2g = (m == 0) ? q2[0] : (m == 1) ? q3[0] : acc[ai][0][m > 1 ? m - 2 : 0][n];
;                     const f32x4 s1v = (m == 0) ? q3[1] : acc[ai][1][m > 0 ? m - 1 : 0][n], s2v = (m == 0) ? q2[1] : (m == 1) ? q3[1] : acc[ai][1][m > 1 ? m - 2 : 0][n];
;                     const f32x4 cgt = bg + wg[0] * s2g + wg[1] * s1g + wg[2] * acc[ai][0][m][n], cvl = bv + wv[0] * s2v + wv[1] * s1v + wv[2] * acc[ai][1][m][n];
.LBB0_984:
	s_or_b64 exec, exec, s[2:3]
	s_lshl_b32 s2, s82, 10
	s_and_b32 s12, s2, 0x400
	v_lshl_add_u32 v165, s12, 2, v206
	s_waitcnt lgkmcnt(0)
	s_barrier
	v_add_u32_e32 v151, s75, v205
	v_pk_mul_f32 v[188:189], v[34:35], v[62:63] op_sel_hi:[1,0]
	v_pk_mul_f32 v[190:191], v[36:37], v[62:63] op_sel_hi:[1,0]
	v_pk_mul_f32 v[166:167], v[30:31], v[62:63] op_sel_hi:[1,0]
	v_pk_mul_f32 v[168:169], v[32:33], v[62:63] op_sel_hi:[1,0]
	v_pk_mul_f32 v[186:187], v[18:19], v[62:63] op_sel_hi:[1,0]
	v_pk_mul_f32 v[192:193], v[20:21], v[62:63] op_sel_hi:[1,0]
	v_pk_mul_f32 v[144:145], v[14:15], v[62:63] op_sel_hi:[1,0]
	v_pk_mul_f32 v[170:171], v[16:17], v[62:63] op_sel_hi:[1,0]
	v_pk_mul_f32 v[180:181], v[26:27], v[62:63] op_sel:[0,1]
	v_pk_mul_f32 v[182:183], v[28:29], v[62:63] op_sel:[0,1]
	v_pk_mul_f32 v[64:65], v[22:23], v[62:63] op_sel:[0,1]
	v_pk_mul_f32 v[142:143], v[24:25], v[62:63] op_sel:[0,1]
	v_pk_mul_f32 v[178:179], v[10:11], v[62:63] op_sel:[0,1]
	v_pk_mul_f32 v[184:185], v[12:13], v[62:63] op_sel:[0,1]
	ds_read_b128 v[26:29], v165
	ds_read_b128 v[30:33], v165 offset:512
	ds_read_b128 v[18:21], v165 offset:2048
	ds_read_b128 v[14:17], v165 offset:2560
	ds_read_b128 v[22:25], v165 offset:1024
	ds_read_b128 v[86:89], v165 offset:1536
	ds_read_b128 v[172:175], v151
	ds_read_b128 v[194:197], v151 offset:16
	ds_read_b128 v[10:13], v165 offset:3072
	ds_read_b128 v[34:37], v165 offset:3584
	v_mov_b32_e32 v147, v146
	s_waitcnt lgkmcnt(0)
	v_pk_mul_f32 v[222:223], v[146:147], v[174:175]
	v_pk_mul_f32 v[224:225], v[148:149], v[172:173]
	v_pk_mul_f32 v[226:227], v[146:147], v[196:197]
	v_pk_mul_f32 v[228:229], v[148:149], v[194:195]
	ds_read_b128 v[172:175], v151 offset:64
	ds_read_b128 v[194:197], v151 offset:80
	v_mov_b32_dpp v224, v134 row_shr:1 row_mask:0xf bank_mask:0xf
	v_mov_b32_dpp v222, v135 row_shr:1 row_mask:0xf bank_mask:0xf
	v_mov_b32_dpp v225, v130 row_shr:1 row_mask:0xf bank_mask:0xf
	v_mov_b32_dpp v223, v131 row_shr:1 row_mask:0xf bank_mask:0xf
	s_waitcnt lgkmcnt(0)
	v_pk_mul_f32 v[232:233], v[146:147], v[196:197]
	v_mov_b32_e32 v196, v224
	v_mov_b32_e32 v197, v222
	v_pk_fma_f32 v[196:197], v[26:27], v[196:197], v[86:87]
	v_mov_b32_e32 v222, v225
	v_pk_mul_f32 v[230:231], v[146:147], v[174:175]
	v_pk_mul_f32 v[172:173], v[148:149], v[172:173]
	v_pk_fma_f32 v[196:197], v[30:31], v[222:223], v[196:197]
	v_mov_b32_dpp v228, v136 row_shr:1 row_mask:0xf bank_mask:0xf
	v_mov_b32_dpp v229, v132 row_shr:1 row_mask:0xf bank_mask:0xf
	v_mov_b32_dpp v226, v137 row_shr:1 row_mask:0xf bank_mask:0xf
	v_mov_b32_dpp v172, v126 row_shr:1 row_mask:0xf bank_mask:0xf
	v_mov_b32_dpp v173, v122 row_shr:1 row_mask:0xf bank_mask:0xf
	v_mov_b32_dpp v230, v127 row_shr:1 row_mask:0xf bank_mask:0xf
	v_pk_fma_f32 v[196:197], v[118:119], v[22:23], v[196:197]
	v_pk_mul_f32 v[174:175], v[148:149], v[194:195]
	v_mov_b32_e32 v194, v228
	v_mov_b32_e32 v195, v226
	v_mov_b32_e32 v226, v229
	v_mov_b32_e32 v228, v172
	v_mov_b32_e32 v229, v230
	v_mov_b32_e32 v230, v173
	v_pk_mul_f32 v[234:235], v[196:197], v[196:197]
	v_mov_b64_e32 v[172:173], s[46:47]
	v_pk_fma_f32 v[234:235], v[234:235], s[44:45], v[172:173] op_sel_hi:[1,0,0] neg_lo:[1,0,0] neg_hi:[1,0,0]
	v_mov_b32_dpp v227, v133 row_shr:1 row_mask:0xf bank_mask:0xf
	v_mov_b32_dpp v174, v128 row_shr:1 row_mask:0xf bank_mask:0xf
	v_mov_b32_dpp v232, v129 row_shr:1 row_mask:0xf bank_mask:0xf
	v_pk_fma_f32 v[194:195], v[28:29], v[194:195], v[88:89]
	v_pk_mul_f32 v[234:235], v[196:197], v[234:235]
	v_mov_b32_dpp v175, v124 row_shr:1 row_mask:0xf bank_mask:0xf
	v_pk_fma_f32 v[194:195], v[32:33], v[226:227], v[194:195]
	v_mov_b32_e32 v224, v174
	v_mov_b32_e32 v225, v232
	v_exp_f32_e32 v234, v234
	v_exp_f32_e32 v235, v235
	v_mov_b32_dpp v231, v123 row_shr:1 row_mask:0xf bank_mask:0xf
	v_mov_b32_dpp v233, v125 row_shr:1 row_mask:0xf bank_mask:0xf
	v_pk_fma_f32 v[194:195], v[120:121], v[24:25], v[194:195]
	v_pk_fma_f32 v[224:225], v[20:21], v[224:225], v[36:37]
	v_pk_fma_f32 v[228:229], v[18:19], v[228:229], v[34:35]
	v_mov_b32_e32 v232, v175
	v_pk_fma_f32 v[174:175], v[16:17], v[232:233], v[224:225]
	v_pk_fma_f32 v[224:225], v[14:15], v[230:231], v[228:229]
	v_pk_mul_f32 v[228:229], v[194:195], v[194:195]
	v_pk_add_f32 v[234:235], v[234:235], 1.0 op_sel_hi:[1,0]
	v_pk_fma_f32 v[228:229], v[228:229], s[44:45], v[172:173] op_sel_hi:[1,0,0] neg_lo:[1,0,0] neg_hi:[1,0,0]
	v_rcp_f32_e32 v234, v234
	v_pk_mul_f32 v[228:229], v[194:195], v[228:229]
	v_rcp_f32_e32 v235, v235
	v_exp_f32_e32 v228, v228
	v_exp_f32_e32 v229, v229
	v_lshl_or_b32 v176, s86, 7, v218
	v_pk_fma_f32 v[224:225], v[138:139], v[10:11], v[224:225]
	v_pk_mul_f32 v[196:197], v[196:197], v[234:235]
	v_pk_add_f32 v[228:229], v[228:229], 1.0 op_sel_hi:[1,0]
	v_ashrrev_i32_e32 v177, 31, v176
	v_rcp_f32_e32 v228, v228
	v_rcp_f32_e32 v229, v229
	v_pk_mul_f32 v[196:197], v[224:225], v[196:197]
	v_pk_fma_f32 v[222:223], v[26:27], v[222:223], v[86:87]
	v_cvt_pk_bf16_f32 v224, v196, v197
	v_lshlrev_b64 v[196:197], 1, v[176:177]
	v_pk_fma_f32 v[176:177], v[28:29], v[226:227], v[88:89]
	v_pk_fma_f32 v[222:223], v[118:119], v[30:31], v[222:223]
	v_pk_fma_f32 v[176:177], v[120:121], v[32:33], v[176:177]
	v_pk_fma_f32 v[222:223], v[106:107], v[22:23], v[222:223]
	v_pk_fma_f32 v[176:177], v[108:109], v[24:25], v[176:177]
	v_pk_mul_f32 v[194:195], v[194:195], v[228:229]
	v_pk_fma_f32 v[226:227], v[18:19], v[230:231], v[34:35]
	v_pk_mul_f32 v[228:229], v[176:177], v[176:177]
	v_pk_mul_f32 v[230:231], v[222:223], v[222:223]
	v_pk_fma_f32 v[228:229], v[228:229], s[44:45], v[172:173] op_sel_hi:[1,0,0] neg_lo:[1,0,0] neg_hi:[1,0,0]
; __device__ __forceinline__ unsigned cvt_pk_bf16(float lo, float hi) { unsigned r; asm volatile("v_cvt_pk_bf16_f32 %0, %1, %2" : "=v"(r) : "v"(lo), "v"(hi)); return r; }
; __device__ __forceinline__ f32x2p gelu_tanh_pk(f32x2p v) { const f32x2p t = v * (v * v * -0.10294324f + -2.3022082f); return v * rcp1p_exp2_pk(t); }
;     __device__ __forceinline__ void operator()(f32x4 (&acc)[2][2][4][2], const Unit& u, const Unit& nxt, bool has_next, int ui, int wr, int wc, int fr, int fq) const {
;     ...
; #pragma unroll
;                 for (int m = 0; m < 4; ++m) { const int row = row0 + ai * HALF + m;
;                     const f32x4 s1g = (m == 0) ? q3[0] : acc[ai][0][m > 0 ? m - 1 : 0][n], s2g = (m == 0) ? q2[0] : (m == 1) ? q3[0] : acc[ai][0][m > 1 ? m - 2 : 0][n];
;                     const f32x4 s1v = (m == 0) ? q3[1] : acc[ai][1][m > 0 ? m - 1 : 0][n], s2v = (m == 0) ? q2[1] : (m == 1) ? q3[1] : acc[ai][1][m > 1 ? m - 2 : 0][n];
;                     const f32x4 cgt = bg + wg[0] * s2g + wg[1] * s1g + wg[2] * acc[ai][0][m][n], cvl = bv + wv[0] * s2v + wv[1] * s1v + wv[2] * acc[ai][1][m][n];
;                     const f32x2p o01 = gelu_tanh_pk((f32x2p){cgt[0], cgt[1]}) * (f32x2p){cvl[0], cvl[1]}, o23 = gelu_tanh_pk((f32x2p){cgt[2], cgt[3]}) * (f32x2p){cvl[2], cvl[3]};
;                     u32x2 w; w.x = cvt_pk_bf16(o01.x, o01.y); w.y = cvt_pk_bf16(o23.x, o23.y);
;                     *(u32x2*)(G + (size_t)row * 12288 + cbase + 4 * n) = w; } } }
	v_pk_fma_f32 v[230:231], v[230:231], s[44:45], v[172:173] op_sel_hi:[1,0,0] neg_lo:[1,0,0] neg_hi:[1,0,0]
	v_pk_mul_f32 v[228:229], v[176:177], v[228:229]
	v_pk_mul_f32 v[230:231], v[222:223], v[230:231]
	v_exp_f32_e32 v228, v228
	v_exp_f32_e32 v230, v230
	v_exp_f32_e32 v231, v231
	v_exp_f32_e32 v229, v229
	v_pk_fma_f32 v[174:175], v[140:141], v[12:13], v[174:175]
	v_pk_fma_f32 v[226:227], v[138:139], v[14:15], v[226:227]
	v_pk_mul_f32 v[174:175], v[174:175], v[194:195]
	v_mov_b64_e32 v[194:195], s[36:37]
	v_pk_add_f32 v[230:231], v[230:231], 1.0 op_sel_hi:[1,0]
	v_pk_add_f32 v[228:229], v[228:229], 1.0 op_sel_hi:[1,0]
	v_cvt_pk_bf16_f32 v225, v174, v175
	v_mad_i64_i32 v[174:175], s[2:3], v164, s69, v[194:195]
	v_rcp_f32_e32 v230, v230
	v_rcp_f32_e32 v231, v231
	v_rcp_f32_e32 v228, v228
	v_rcp_f32_e32 v229, v229
	v_lshl_add_u64 v[174:175], v[174:175], 0, v[196:197]
	global_store_dwordx2 v[174:175], v[224:225], off
	v_pk_fma_f32 v[224:225], v[20:21], v[232:233], v[36:37]
	v_pk_fma_f32 v[226:227], v[78:79], v[10:11], v[226:227]
	v_pk_fma_f32 v[224:225], v[140:141], v[16:17], v[224:225]
	v_pk_mul_f32 v[222:223], v[222:223], v[230:231]
	v_pk_fma_f32 v[224:225], v[80:81], v[12:13], v[224:225]
	v_pk_mul_f32 v[176:177], v[176:177], v[228:229]
	v_or_b32_e32 v151, 1, v164
	v_pk_mul_f32 v[222:223], v[226:227], v[222:223]
	v_pk_mul_f32 v[176:177], v[224:225], v[176:177]
	v_pk_fma_f32 v[120:121], v[120:121], v[28:29], v[88:89]
	v_cvt_pk_bf16_f32 v222, v222, v223
	v_cvt_pk_bf16_f32 v223, v176, v177
	v_mad_i64_i32 v[176:177], s[2:3], v151, s69, v[194:195]
	v_pk_fma_f32 v[118:119], v[118:119], v[26:27], v[86:87]
	v_pk_fma_f32 v[120:121], v[108:109], v[32:33], v[120:121]
	v_lshl_add_u64 v[176:177], v[176:177], 0, v[196:197]
	v_pk_fma_f32 v[118:119], v[106:107], v[30:31], v[118:119]
	v_pk_fma_f32 v[120:121], v[136:137], v[24:25], v[120:121]
	global_store_dwordx2 v[176:177], v[222:223], off
	v_pk_fma_f32 v[118:119], v[134:135], v[22:23], v[118:119]
	v_pk_mul_f32 v[222:223], v[120:121], v[120:121]
	v_pk_mul_f32 v[224:225], v[118:119], v[118:119]
	v_pk_fma_f32 v[222:223], v[222:223], s[44:45], v[172:173] op_sel_hi:[1,0,0] neg_lo:[1,0,0] neg_hi:[1,0,0]
	v_pk_fma_f32 v[224:225], v[224:225], s[44:45], v[172:173] op_sel_hi:[1,0,0] neg_lo:[1,0,0] neg_hi:[1,0,0]
	v_pk_mul_f32 v[222:223], v[120:121], v[222:223]
	v_pk_mul_f32 v[224:225], v[118:119], v[224:225]
	v_exp_f32_e32 v222, v222
	v_exp_f32_e32 v223, v223
	v_exp_f32_e32 v224, v224
	v_exp_f32_e32 v225, v225
	v_pk_fma_f32 v[140:141], v[140:141], v[20:21], v[36:37]
	v_pk_add_f32 v[222:223], v[222:223], 1.0 op_sel_hi:[1,0]
	v_pk_fma_f32 v[106:107], v[106:107], v[26:27], v[86:87]
	v_pk_add_f32 v[224:225], v[224:225], 1.0 op_sel_hi:[1,0]
	v_rcp_f32_e32 v222, v222
	v_rcp_f32_e32 v223, v223
	v_rcp_f32_e32 v224, v224
	v_rcp_f32_e32 v225, v225
	v_pk_fma_f32 v[138:139], v[138:139], v[18:19], v[34:35]
	v_pk_fma_f32 v[140:141], v[80:81], v[16:17], v[140:141]
	v_pk_fma_f32 v[108:109], v[108:109], v[28:29], v[88:89]
	v_pk_fma_f32 v[106:107], v[134:135], v[30:31], v[106:107]
	v_pk_fma_f32 v[80:81], v[80:81], v[20:21], v[36:37]
	v_pk_fma_f32 v[138:139], v[78:79], v[14:15], v[138:139]
	v_pk_fma_f32 v[140:141], v[128:129], v[12:13], v[140:141]
	v_pk_mul_f32 v[120:121], v[120:121], v[222:223]
	v_pk_fma_f32 v[108:109], v[136:137], v[32:33], v[108:109]
	v_pk_fma_f32 v[106:107], v[130:131], v[22:23], v[106:107]
	v_pk_fma_f32 v[80:81], v[128:129], v[16:17], v[80:81]
	v_pk_fma_f32 v[138:139], v[126:127], v[10:11], v[138:139]
	v_pk_mul_f32 v[118:119], v[118:119], v[224:225]
	v_pk_mul_f32 v[120:121], v[140:141], v[120:121]
	v_pk_fma_f32 v[108:109], v[132:133], v[24:25], v[108:109]
	v_pk_fma_f32 v[80:81], v[124:125], v[12:13], v[80:81]
	v_pk_mul_f32 v[124:125], v[106:107], v[106:107]
	v_pk_mul_f32 v[118:119], v[138:139], v[118:119]
	v_pk_fma_f32 v[124:125], v[124:125], s[44:45], v[172:173] op_sel_hi:[1,0,0] neg_lo:[1,0,0] neg_hi:[1,0,0]
	v_cvt_pk_bf16_f32 v138, v118, v119
	v_cvt_pk_bf16_f32 v139, v120, v121
	v_pk_mul_f32 v[120:121], v[108:109], v[108:109]
	v_pk_mul_f32 v[124:125], v[106:107], v[124:125]
	v_pk_fma_f32 v[120:121], v[120:121], s[44:45], v[172:173] op_sel_hi:[1,0,0] neg_lo:[1,0,0] neg_hi:[1,0,0]
	v_exp_f32_e32 v124, v124
	v_exp_f32_e32 v125, v125
	v_pk_mul_f32 v[120:121], v[108:109], v[120:121]
	v_pk_fma_f32 v[78:79], v[78:79], v[18:19], v[34:35]
	v_exp_f32_e32 v120, v120
	v_exp_f32_e32 v121, v121
	v_pk_add_f32 v[124:125], v[124:125], 1.0 op_sel_hi:[1,0]
	v_or_b32_e32 v151, 2, v164
	v_rcp_f32_e32 v124, v124
	v_rcp_f32_e32 v125, v125
	v_pk_add_f32 v[120:121], v[120:121], 1.0 op_sel_hi:[1,0]
	v_pk_fma_f32 v[78:79], v[126:127], v[14:15], v[78:79]
	v_rcp_f32_e32 v120, v120
	v_rcp_f32_e32 v121, v121
	v_mad_i64_i32 v[118:119], s[2:3], v151, s69, v[194:195]
	v_pk_fma_f32 v[78:79], v[122:123], v[10:11], v[78:79]
	v_pk_mul_f32 v[106:107], v[106:107], v[124:125]
	v_lshl_add_u64 v[118:119], v[118:119], 0, v[196:197]
	v_pk_mul_f32 v[78:79], v[78:79], v[106:107]
	v_pk_mul_f32 v[106:107], v[108:109], v[120:121]
	v_add_u32_e32 v130, s76, v205
	global_store_dwordx2 v[118:119], v[138:139], off
	v_pk_mul_f32 v[80:81], v[80:81], v[106:107]
	v_cvt_pk_bf16_f32 v124, v78, v79
	v_or_b32_e32 v138, 3, v164
	v_cvt_pk_bf16_f32 v125, v80, v81
	ds_read_b128 v[106:109], v130
	ds_read_b128 v[120:123], v130 offset:16
	v_mad_i64_i32 v[78:79], s[2:3], v138, s69, v[194:195]
	v_lshl_add_u64 v[78:79], v[78:79], 0, v[196:197]
	v_mov_b32_e32 v151, v150
	global_store_dwordx2 v[78:79], v[124:125], off
	s_waitcnt lgkmcnt(0)
; #define PG8_LAS __attribute__((address_space(3)))
; __device__ __forceinline__ unsigned cvt_pk_bf16(float lo, float hi) { unsigned r; asm volatile("v_cvt_pk_bf16_f32 %0, %1, %2" : "=v"(r) : "v"(lo), "v"(hi)); return r; }
;     __device__ __forceinline__ void operator()(f32x4 (&acc)[2][2][4][2], const Unit& u, const Unit& nxt, bool has_next, int ui, int wr, int wc, int fr, int fq) const {
;     ...
;             for (int ai = 0; ai < 2; ++ai) { const int blk = 2 * ai + wr; const int pblk = blk > 0 ? blk - 1 : 0; const float hz = blk > 0 ? 1.0f : 0.0f;
;                 f32x4 q2[2], q3[2];
; #pragma unroll
;                 for (int bj = 0; bj < 2; ++bj) {
;                     const PG8_LAS f32x4* hp = (const PG8_LAS f32x4*)(halo + ((pblk * 4 + wc) * 4 + fq) * 32 + (bj * 8 + n * 4) * 2);
;                     const f32x4 ha = hp[0] * hz, hb = hp[1] * hz;
;                     q2[bj][0] = dpp_shr1(ha[0], acc[ai][bj][2][n][0]); q3[bj][0] = dpp_shr1(ha[1], acc[ai][bj][3][n][0]);
;                     q2[bj][1] = dpp_shr1(ha[2], acc[ai][bj][2][n][1]); q3[bj][1] = dpp_shr1(ha[3], acc[ai][bj][3][n][1]);
;                     q2[bj][2] = dpp_shr1(hb[0], acc[ai][bj][2][n][2]); q3[bj][2] = dpp_shr1(hb[1], acc[ai][bj][3][n][2]);
;                     q2[bj][3] = dpp_shr1(hb[2], acc[ai][bj][2][n][3]); q3[bj][3] = dpp_shr1(hb[3], acc[ai][bj][3][n][3]); }
; #pragma unroll
;                 for (int m = 0; m < 4; ++m) { const int row = row0 + ai * HALF + m;
;                     const f32x4 s1g = (m == 0) ? q3[0] : acc[ai][0][m > 0 ? m - 1 : 0][n], s2g = (m == 0) ? q2[0] : (m == 1) ? q3[0] : acc[ai][0][m > 1 ? m - 2 : 0][n];
;                     const f32x4 s1v = (m == 0) ? q3[1] : acc[ai][1][m > 0 ? m - 1 : 0][n], s2v = (m == 0) ? q2[1] : (m == 1) ? q3[1] : acc[ai][1][m > 1 ? m - 2 : 0][n];
;                     const f32x4 cgt = bg + wg[0] * s2g + wg[1] * s1g + wg[2] * acc[ai][0][m][n], cvl = bv + wv[0] * s2v + wv[1] * s1v + wv[2] * acc[ai][1][m][n];
;                     const f32x2p o01 = gelu_tanh_pk((f32x2p){cgt[0], cgt[1]}) * (f32x2p){cvl[0], cvl[1]}, o23 = gelu_tanh_pk((f32x2p){cgt[2], cgt[3]}) * (f32x2p){cvl[2], cvl[3]};
;                     u32x2 w; w.x = cvt_pk_bf16(o01.x, o01.y); w.y = cvt_pk_bf16(o23.x, o23.y);
;                     *(u32x2*)(G + (size_t)row * 12288 + cbase + 4 * n) = w; } } }
	v_pk_mul_f32 v[124:125], v[150:151], v[108:109]
	v_pk_mul_f32 v[80:81], v[152:153], v[106:107]
	ds_read_b128 v[106:109], v130 offset:64
	v_pk_mul_f32 v[126:127], v[150:151], v[122:123]
	v_pk_mul_f32 v[128:129], v[152:153], v[120:121]
	ds_read_b128 v[120:123], v130 offset:80
	v_mov_b32_dpp v80, v70 row_shr:1 row_mask:0xf bank_mask:0xf
	v_mov_b32_dpp v124, v71 row_shr:1 row_mask:0xf bank_mask:0xf
	v_mov_b32_dpp v81, v58 row_shr:1 row_mask:0xf bank_mask:0xf
	v_mov_b32_dpp v128, v72 row_shr:1 row_mask:0xf bank_mask:0xf
	v_mov_b32_dpp v126, v73 row_shr:1 row_mask:0xf bank_mask:0xf
	s_waitcnt lgkmcnt(0)
	v_pk_mul_f32 v[108:109], v[150:151], v[108:109]
	v_pk_mul_f32 v[106:107], v[152:153], v[106:107]
	v_mov_b32_e32 v132, v80
	v_mov_b32_e32 v133, v124
	v_mov_b32_dpp v125, v59 row_shr:1 row_mask:0xf bank_mask:0xf
	v_mov_b32_dpp v129, v60 row_shr:1 row_mask:0xf bank_mask:0xf
	v_pk_mul_f32 v[122:123], v[150:151], v[122:123]
	v_pk_mul_f32 v[120:121], v[152:153], v[120:121]
	v_mov_b32_dpp v106, v54 row_shr:1 row_mask:0xf bank_mask:0xf
	v_mov_b32_dpp v108, v55 row_shr:1 row_mask:0xf bank_mask:0xf
	v_mov_b32_e32 v130, v128
	v_mov_b32_e32 v131, v126
	v_pk_fma_f32 v[132:133], v[26:27], v[132:133], v[86:87]
	v_mov_b32_e32 v124, v81
	v_mov_b32_dpp v127, v61 row_shr:1 row_mask:0xf bank_mask:0xf
	v_mov_b32_dpp v107, v42 row_shr:1 row_mask:0xf bank_mask:0xf
	v_mov_b32_dpp v120, v56 row_shr:1 row_mask:0xf bank_mask:0xf
	v_mov_b32_dpp v122, v57 row_shr:1 row_mask:0xf bank_mask:0xf
	v_pk_fma_f32 v[130:131], v[28:29], v[130:131], v[88:89]
	v_mov_b32_e32 v126, v129
	v_pk_fma_f32 v[80:81], v[30:31], v[124:125], v[132:133]
	v_mov_b32_e32 v132, v106
	v_mov_b32_e32 v133, v108
	v_mov_b32_dpp v109, v43 row_shr:1 row_mask:0xf bank_mask:0xf
	v_mov_b32_dpp v121, v44 row_shr:1 row_mask:0xf bank_mask:0xf
	v_pk_fma_f32 v[128:129], v[32:33], v[126:127], v[130:131]
	v_pk_fma_f32 v[80:81], v[188:189], v[22:23], v[80:81]
	v_mov_b32_e32 v130, v120
	v_mov_b32_e32 v131, v122
	v_pk_fma_f32 v[132:133], v[18:19], v[132:133], v[34:35]
	v_mov_b32_e32 v108, v107
	v_mov_b32_dpp v123, v45 row_shr:1 row_mask:0xf bank_mask:0xf
	v_pk_fma_f32 v[128:129], v[190:191], v[24:25], v[128:129]
	v_pk_fma_f32 v[130:131], v[20:21], v[130:131], v[36:37]
	v_mov_b32_e32 v122, v121
	v_pk_fma_f32 v[106:107], v[14:15], v[108:109], v[132:133]
	v_pk_mul_f32 v[132:133], v[80:81], v[80:81]
	v_pk_fma_f32 v[120:121], v[16:17], v[122:123], v[130:131]
	v_pk_mul_f32 v[130:131], v[128:129], v[128:129]
	v_pk_fma_f32 v[132:133], v[132:133], s[44:45], v[172:173] op_sel_hi:[1,0,0] neg_lo:[1,0,0] neg_hi:[1,0,0]
	v_pk_fma_f32 v[130:131], v[130:131], s[44:45], v[172:173] op_sel_hi:[1,0,0] neg_lo:[1,0,0] neg_hi:[1,0,0]
	v_pk_mul_f32 v[132:133], v[80:81], v[132:133]
	v_pk_mul_f32 v[130:131], v[128:129], v[130:131]
	v_exp_f32_e32 v132, v132
	v_exp_f32_e32 v133, v133
	v_exp_f32_e32 v130, v130
	v_exp_f32_e32 v131, v131
	v_pk_fma_f32 v[106:107], v[186:187], v[10:11], v[106:107]
	v_pk_add_f32 v[132:133], v[132:133], 1.0 op_sel_hi:[1,0]
	v_add_u32_e32 v134, 0x80, v164
	v_rcp_f32_e32 v132, v132
	v_rcp_f32_e32 v133, v133
	v_pk_add_f32 v[130:131], v[130:131], 1.0 op_sel_hi:[1,0]
	v_pk_fma_f32 v[120:121], v[192:193], v[12:13], v[120:121]
	v_rcp_f32_e32 v130, v130
	v_rcp_f32_e32 v131, v131
	v_pk_mul_f32 v[80:81], v[80:81], v[132:133]
	v_pk_fma_f32 v[122:123], v[20:21], v[122:123], v[36:37]
	v_pk_mul_f32 v[80:81], v[106:107], v[80:81]
	v_pk_mul_f32 v[106:107], v[128:129], v[130:131]
	v_pk_fma_f32 v[108:109], v[18:19], v[108:109], v[34:35]
	v_pk_mul_f32 v[106:107], v[120:121], v[106:107]
	v_cvt_pk_bf16_f32 v120, v80, v81
	v_mad_i64_i32 v[80:81], s[2:3], v134, s69, v[194:195]
	v_cvt_pk_bf16_f32 v121, v106, v107
	v_lshl_add_u64 v[80:81], v[80:81], 0, v[196:197]
	global_store_dwordx2 v[80:81], v[120:121], off
	v_pk_fma_f32 v[106:107], v[28:29], v[126:127], v[88:89]
	v_pk_fma_f32 v[120:121], v[26:27], v[124:125], v[86:87]
	v_pk_fma_f32 v[106:107], v[190:191], v[32:33], v[106:107]
	v_pk_fma_f32 v[120:121], v[188:189], v[30:31], v[120:121]
	v_pk_fma_f32 v[106:107], v[182:183], v[24:25], v[106:107]
	v_pk_fma_f32 v[120:121], v[180:181], v[22:23], v[120:121]
	v_pk_mul_f32 v[124:125], v[106:107], v[106:107]
	v_pk_mul_f32 v[126:127], v[120:121], v[120:121]
	v_pk_fma_f32 v[124:125], v[124:125], s[44:45], v[172:173] op_sel_hi:[1,0,0] neg_lo:[1,0,0] neg_hi:[1,0,0]
	v_pk_fma_f32 v[126:127], v[126:127], s[44:45], v[172:173] op_sel_hi:[1,0,0] neg_lo:[1,0,0] neg_hi:[1,0,0]
	v_pk_mul_f32 v[124:125], v[106:107], v[124:125]
	v_pk_mul_f32 v[126:127], v[120:121], v[126:127]
	v_exp_f32_e32 v124, v124
	v_exp_f32_e32 v126, v126
	v_exp_f32_e32 v127, v127
	v_exp_f32_e32 v125, v125
	v_pk_fma_f32 v[122:123], v[192:193], v[16:17], v[122:123]
	v_pk_fma_f32 v[108:109], v[186:187], v[14:15], v[108:109]
	v_pk_add_f32 v[126:127], v[126:127], 1.0 op_sel_hi:[1,0]
	v_pk_add_f32 v[124:125], v[124:125], 1.0 op_sel_hi:[1,0]
	v_rcp_f32_e32 v126, v126
	v_rcp_f32_e32 v127, v127
	v_rcp_f32_e32 v124, v124
	v_rcp_f32_e32 v125, v125
	v_pk_fma_f32 v[122:123], v[184:185], v[12:13], v[122:123]
	v_pk_fma_f32 v[108:109], v[178:179], v[10:11], v[108:109]
	v_pk_mul_f32 v[120:121], v[120:121], v[126:127]
	v_pk_mul_f32 v[106:107], v[106:107], v[124:125]
	v_add_u32_e32 v128, 0x81, v164
	v_pk_mul_f32 v[108:109], v[108:109], v[120:121]
	v_pk_mul_f32 v[106:107], v[122:123], v[106:107]
	v_cvt_pk_bf16_f32 v108, v108, v109
	v_pk_fma_f32 v[120:121], v[190:191], v[28:29], v[88:89]
	v_cvt_pk_bf16_f32 v109, v106, v107
	v_mad_i64_i32 v[106:107], s[2:3], v128, s69, v[194:195]
	v_lshl_add_u64 v[106:107], v[106:107], 0, v[196:197]
	global_store_dwordx2 v[106:107], v[108:109], off
	v_pk_fma_f32 v[108:109], v[188:189], v[26:27], v[86:87]
; #define PG8_LAS __attribute__((address_space(3)))
;     __device__ __forceinline__ void operator()(f32x4 (&acc)[2][2][4][2], const Unit& u, const Unit& nxt, bool has_next, int ui, int wr, int wc, int fr, int fq) const {
;     ...
;         for (int n = 0; n < 2; ++n) {
;             f32x4 wg[3], wv[3];
; #pragma unroll
;             for (int k = 0; k < 3; ++k) { wg[k] = *(const PG8_LAS f32x4*)(tab + k * 128 + 4 * n); wv[k] = *(const PG8_LAS f32x4*)(tab + (4 + k) * 128 + 4 * n); }
;             const f32x4 bg = *(const PG8_LAS f32x4*)(tab + 3 * 128 + 4 * n), bv = *(const PG8_LAS f32x4*)(tab + 7 * 128 + 4 * n);
; #pragma unroll
;             for (int ai = 0; ai < 2; ++ai) { const int blk = 2 * ai + wr; const int pblk = blk > 0 ? blk - 1 : 0; const float hz = blk > 0 ? 1.0f : 0.0f;
;                 f32x4 q2[2], q3[2];
; #pragma unroll
;                 for (int bj = 0; bj < 2; ++bj) {
;                     const PG8_LAS f32x4* hp = (const PG8_LAS f32x4*)(halo + ((pblk * 4 + wc) * 4 + fq) * 32 + (bj * 8 + n * 4) * 2);
;                     const f32x4 ha = hp[0] * hz, hb = hp[1] * hz;
;                     q2[bj][0] = dpp_shr1(ha[0], acc[ai][bj][2][n][0]); q3[bj][0] = dpp_shr1(ha[1], acc[ai][bj][3][n][0]);
;                     q2[bj][1] = dpp_shr1(ha[2], acc[ai][bj][2][n][1]); q3[bj][1] = dpp_shr1(ha[3], acc[ai][bj][3][n][1]);
;                     q2[bj][2] = dpp_shr1(hb[0], acc[ai][bj][2][n][2]); q3[bj][2] = dpp_shr1(hb[1], acc[ai][bj][3][n][2]);
;                     q2[bj][3] = dpp_shr1(hb[2], acc[ai][bj][2][n][3]); q3[bj][3] = dpp_shr1(hb[3], acc[ai][bj][3][n][3]); }
; #pragma unroll
;                 for (int m = 0; m < 4; ++m) { const int row = row0 + ai * HALF + m;
;                     const f32x4 s1g = (m == 0) ? q3[0] : acc[ai][0][m > 0 ? m - 1 : 0][n], s2g = (m == 0) ? q2[0] : (m == 1) ? q3[0] : acc[ai][0][m > 1 ? m - 2 : 0][n];
;                     const f32x4 s1v = (m == 0) ? q3[1] : acc[ai][1][m > 0 ? m - 1 : 0][n], s2v = (m == 0) ? q2[1] : (m == 1) ? q3[1] : acc[ai][1][m > 1 ? m - 2 : 0][n];
;                     const f32x4 cgt = bg + wg[0] * s2g + wg[1] * s1g + wg[2] * acc[ai][0][m][n], cvl = bv + wv[0] * s2v + wv[1] * s1v + wv[2] * acc[ai][1][m][n];
;                     const f32x2p o01 = gelu_tanh_pk((f32x2p){cgt[0], cgt[1]}) * (f32x2p){cvl[0], cvl[1]}, o23 = gelu_tanh_pk((f32x2p){cgt[2], cgt[3]}) * (f32x2p){cvl[2], cvl[3]};
	v_pk_fma_f32 v[26:27], v[180:181], v[26:27], v[86:87]
	v_pk_fma_f32 v[108:109], v[180:181], v[30:31], v[108:109]
	v_pk_fma_f32 v[120:121], v[182:183], v[32:33], v[120:121]
	v_pk_fma_f32 v[108:109], v[70:71], v[22:23], v[108:109]
	v_pk_fma_f32 v[28:29], v[182:183], v[28:29], v[88:89]
	v_pk_fma_f32 v[26:27], v[70:71], v[30:31], v[26:27]
	v_pk_fma_f32 v[120:121], v[72:73], v[24:25], v[120:121]
	v_pk_fma_f32 v[122:123], v[192:193], v[20:21], v[36:37]
	v_pk_fma_f32 v[124:125], v[186:187], v[18:19], v[34:35]
	v_pk_mul_f32 v[128:129], v[108:109], v[108:109]
	v_pk_fma_f32 v[28:29], v[72:73], v[32:33], v[28:29]
	v_pk_fma_f32 v[22:23], v[58:59], v[22:23], v[26:27]
	v_pk_fma_f32 v[20:21], v[184:185], v[20:21], v[36:37]
	v_pk_fma_f32 v[18:19], v[178:179], v[18:19], v[34:35]
	v_pk_fma_f32 v[124:125], v[178:179], v[14:15], v[124:125]
	v_pk_fma_f32 v[122:123], v[184:185], v[16:17], v[122:123]
	v_pk_mul_f32 v[126:127], v[120:121], v[120:121]
	v_pk_fma_f32 v[128:129], v[128:129], s[44:45], v[172:173] op_sel_hi:[1,0,0] neg_lo:[1,0,0] neg_hi:[1,0,0]
	v_pk_fma_f32 v[24:25], v[60:61], v[24:25], v[28:29]
	v_pk_fma_f32 v[14:15], v[54:55], v[14:15], v[18:19]
	v_pk_fma_f32 v[16:17], v[56:57], v[16:17], v[20:21]
	v_pk_mul_f32 v[18:19], v[22:23], v[22:23]
	v_pk_fma_f32 v[122:123], v[56:57], v[12:13], v[122:123]
	v_pk_mul_f32 v[128:129], v[108:109], v[128:129]
	v_pk_fma_f32 v[126:127], v[126:127], s[44:45], v[172:173] op_sel_hi:[1,0,0] neg_lo:[1,0,0] neg_hi:[1,0,0]
	v_pk_fma_f32 v[12:13], v[44:45], v[12:13], v[16:17]
	v_pk_mul_f32 v[16:17], v[24:25], v[24:25]
	v_pk_fma_f32 v[18:19], v[18:19], s[44:45], v[172:173] op_sel_hi:[1,0,0] neg_lo:[1,0,0] neg_hi:[1,0,0]
	v_exp_f32_e32 v128, v128
	v_exp_f32_e32 v129, v129
	v_pk_mul_f32 v[126:127], v[120:121], v[126:127]
	v_pk_mul_f32 v[18:19], v[22:23], v[18:19]
	v_pk_fma_f32 v[16:17], v[16:17], s[44:45], v[172:173] op_sel_hi:[1,0,0] neg_lo:[1,0,0] neg_hi:[1,0,0]
	v_exp_f32_e32 v126, v126
	v_exp_f32_e32 v127, v127
	v_exp_f32_e32 v18, v18
	v_exp_f32_e32 v19, v19
	v_pk_mul_f32 v[16:17], v[24:25], v[16:17]
	v_pk_add_f32 v[128:129], v[128:129], 1.0 op_sel_hi:[1,0]
	v_exp_f32_e32 v16, v16
	v_exp_f32_e32 v17, v17
	v_rcp_f32_e32 v128, v128
	v_rcp_f32_e32 v129, v129
	v_pk_add_f32 v[126:127], v[126:127], 1.0 op_sel_hi:[1,0]
	v_pk_add_f32 v[18:19], v[18:19], 1.0 op_sel_hi:[1,0]
	v_rcp_f32_e32 v126, v126
	v_rcp_f32_e32 v127, v127
	v_rcp_f32_e32 v18, v18
	v_rcp_f32_e32 v19, v19
	v_pk_add_f32 v[16:17], v[16:17], 1.0 op_sel_hi:[1,0]
	v_pk_fma_f32 v[124:125], v[54:55], v[10:11], v[124:125]
	v_rcp_f32_e32 v16, v16
	v_rcp_f32_e32 v17, v17
	v_pk_mul_f32 v[108:109], v[108:109], v[128:129]
	v_add_u32_e32 v130, 0x82, v164
	v_pk_mul_f32 v[108:109], v[124:125], v[108:109]
	v_pk_mul_f32 v[120:121], v[120:121], v[126:127]
	v_pk_fma_f32 v[10:11], v[42:43], v[10:11], v[14:15]
	v_pk_mul_f32 v[14:15], v[22:23], v[18:19]
	v_pk_mul_f32 v[120:121], v[122:123], v[120:121]
	v_cvt_pk_bf16_f32 v122, v108, v109
	v_mad_i64_i32 v[108:109], s[2:3], v130, s69, v[194:195]
	v_pk_mul_f32 v[10:11], v[10:11], v[14:15]
	v_pk_mul_f32 v[14:15], v[24:25], v[16:17]
	v_cvt_pk_bf16_f32 v123, v120, v121
	v_lshl_add_u64 v[108:109], v[108:109], 0, v[196:197]
	v_add_u32_e32 v120, 0x83, v164
	v_pk_mul_f32 v[12:13], v[12:13], v[14:15]
	global_store_dwordx2 v[108:109], v[122:123], off
	v_cvt_pk_bf16_f32 v10, v10, v11
	v_cvt_pk_bf16_f32 v11, v12, v13
	v_mad_i64_i32 v[12:13], s[2:3], v120, s69, v[194:195]
	v_lshl_add_u64 v[54:55], v[12:13], 0, v[196:197]
	global_store_dwordx2 v[54:55], v[10:11], off
	ds_read_b128 v[22:25], v165 offset:16
	ds_read_b128 v[26:29], v165 offset:528
	ds_read_b128 v[18:21], v165 offset:2064
	ds_read_b128 v[14:17], v165 offset:2576
	ds_read_b128 v[56:59], v210
	ds_read_b128 v[30:33], v165 offset:1040
	ds_read_b128 v[42:45], v165 offset:1552
	ds_read_b128 v[70:73], v211
	ds_read_b128 v[10:13], v165 offset:3088
	ds_read_b128 v[34:37], v165 offset:3600
	s_waitcnt lgkmcnt(0)
	v_pk_mul_f32 v[60:61], v[146:147], v[58:59]
	v_pk_mul_f32 v[86:87], v[148:149], v[56:57]
	ds_read_b128 v[56:59], v212
	v_pk_mul_f32 v[88:89], v[146:147], v[72:73]
	v_pk_mul_f32 v[120:121], v[148:149], v[70:71]
	ds_read_b128 v[70:73], v213
	v_mov_b32_dpp v86, v90 row_shr:1 row_mask:0xf bank_mask:0xf
	v_mov_b32_dpp v60, v91 row_shr:1 row_mask:0xf bank_mask:0xf
	v_mov_b32_dpp v87, v110 row_shr:1 row_mask:0xf bank_mask:0xf
	v_mov_b32_dpp v120, v92 row_shr:1 row_mask:0xf bank_mask:0xf
	v_mov_b32_dpp v88, v93 row_shr:1 row_mask:0xf bank_mask:0xf
	s_waitcnt lgkmcnt(0)
; __device__ __forceinline__ unsigned cvt_pk_bf16(float lo, float hi) { unsigned r; asm volatile("v_cvt_pk_bf16_f32 %0, %1, %2" : "=v"(r) : "v"(lo), "v"(hi)); return r; }
; __device__ __forceinline__ f32x2p gelu_tanh_pk(f32x2p v) { const f32x2p t = v * (v * v * -0.10294324f + -2.3022082f); return v * rcp1p_exp2_pk(t); }
;     __device__ __forceinline__ void operator()(f32x4 (&acc)[2][2][4][2], const Unit& u, const Unit& nxt, bool has_next, int ui, int wr, int wc, int fr, int fq) const {
;     ...
; #pragma unroll
;                 for (int m = 0; m < 4; ++m) { const int row = row0 + ai * HALF + m;
;                     const f32x4 s1g = (m == 0) ? q3[0] : acc[ai][0][m > 0 ? m - 1 : 0][n], s2g = (m == 0) ? q2[0] : (m == 1) ? q3[0] : acc[ai][0][m > 1 ? m - 2 : 0][n];
;                     const f32x4 s1v = (m == 0) ? q3[1] : acc[ai][1][m > 0 ? m - 1 : 0][n], s2v = (m == 0) ? q2[1] : (m == 1) ? q3[1] : acc[ai][1][m > 1 ? m - 2 : 0][n];
;                     const f32x4 cgt = bg + wg[0] * s2g + wg[1] * s1g + wg[2] * acc[ai][0][m][n], cvl = bv + wv[0] * s2v + wv[1] * s1v + wv[2] * acc[ai][1][m][n];
;                     const f32x2p o01 = gelu_tanh_pk((f32x2p){cgt[0], cgt[1]}) * (f32x2p){cvl[0], cvl[1]}, o23 = gelu_tanh_pk((f32x2p){cgt[2], cgt[3]}) * (f32x2p){cvl[2], cvl[3]};
;                     u32x2 w; w.x = cvt_pk_bf16(o01.x, o01.y); w.y = cvt_pk_bf16(o23.x, o23.y);
;                     *(u32x2*)(G + (size_t)row * 12288 + cbase + 4 * n) = w; } } }
	v_pk_mul_f32 v[58:59], v[146:147], v[58:59]
	v_pk_mul_f32 v[56:57], v[148:149], v[56:57]
	v_mov_b32_e32 v124, v86
	v_mov_b32_e32 v125, v60
	v_mov_b32_dpp v61, v111 row_shr:1 row_mask:0xf bank_mask:0xf
	v_mov_b32_dpp v121, v112 row_shr:1 row_mask:0xf bank_mask:0xf
	v_pk_mul_f32 v[72:73], v[146:147], v[72:73]
	v_pk_mul_f32 v[70:71], v[148:149], v[70:71]
	v_mov_b32_dpp v56, v98 row_shr:1 row_mask:0xf bank_mask:0xf
	v_mov_b32_dpp v58, v99 row_shr:1 row_mask:0xf bank_mask:0xf
	v_mov_b32_e32 v122, v120
	v_mov_b32_e32 v123, v88
	v_pk_fma_f32 v[124:125], v[22:23], v[124:125], v[42:43]
	v_mov_b32_e32 v60, v87
	v_mov_b32_dpp v89, v113 row_shr:1 row_mask:0xf bank_mask:0xf
	v_mov_b32_dpp v57, v102 row_shr:1 row_mask:0xf bank_mask:0xf
	v_mov_b32_dpp v70, v100 row_shr:1 row_mask:0xf bank_mask:0xf
	v_mov_b32_dpp v72, v101 row_shr:1 row_mask:0xf bank_mask:0xf
	v_pk_fma_f32 v[122:123], v[24:25], v[122:123], v[44:45]
	v_mov_b32_e32 v88, v121
	v_pk_fma_f32 v[86:87], v[26:27], v[60:61], v[124:125]
	v_mov_b32_e32 v124, v56
	v_mov_b32_e32 v125, v58
	v_mov_b32_dpp v59, v103 row_shr:1 row_mask:0xf bank_mask:0xf
	v_mov_b32_dpp v71, v104 row_shr:1 row_mask:0xf bank_mask:0xf
	v_pk_fma_f32 v[120:121], v[28:29], v[88:89], v[122:123]
	v_pk_fma_f32 v[86:87], v[114:115], v[30:31], v[86:87]
	v_mov_b32_e32 v122, v70
	v_mov_b32_e32 v123, v72
	v_pk_fma_f32 v[124:125], v[18:19], v[124:125], v[34:35]
	v_mov_b32_e32 v58, v57
	v_mov_b32_dpp v73, v105 row_shr:1 row_mask:0xf bank_mask:0xf
	v_pk_fma_f32 v[120:121], v[116:117], v[32:33], v[120:121]
	v_pk_fma_f32 v[122:123], v[20:21], v[122:123], v[36:37]
	v_mov_b32_e32 v72, v71
	v_pk_fma_f32 v[56:57], v[14:15], v[58:59], v[124:125]
	v_pk_mul_f32 v[124:125], v[86:87], v[86:87]
	v_pk_fma_f32 v[70:71], v[16:17], v[72:73], v[122:123]
	v_pk_mul_f32 v[122:123], v[120:121], v[120:121]
	v_pk_fma_f32 v[124:125], v[124:125], s[44:45], v[172:173] op_sel_hi:[1,0,0] neg_lo:[1,0,0] neg_hi:[1,0,0]
	v_pk_fma_f32 v[122:123], v[122:123], s[44:45], v[172:173] op_sel_hi:[1,0,0] neg_lo:[1,0,0] neg_hi:[1,0,0]
	v_pk_mul_f32 v[124:125], v[86:87], v[124:125]
	v_pk_mul_f32 v[122:123], v[120:121], v[122:123]
	v_exp_f32_e32 v124, v124
	v_exp_f32_e32 v125, v125
	v_exp_f32_e32 v122, v122
	v_exp_f32_e32 v123, v123
	v_pk_fma_f32 v[56:57], v[94:95], v[10:11], v[56:57]
	v_pk_add_f32 v[124:125], v[124:125], 1.0 op_sel_hi:[1,0]
	v_pk_fma_f32 v[70:71], v[96:97], v[12:13], v[70:71]
	v_rcp_f32_e32 v124, v124
	v_rcp_f32_e32 v125, v125
	v_pk_add_f32 v[122:123], v[122:123], 1.0 op_sel_hi:[1,0]
	v_pk_fma_f32 v[60:61], v[22:23], v[60:61], v[42:43]
	v_rcp_f32_e32 v122, v122
	v_rcp_f32_e32 v123, v123
	v_pk_mul_f32 v[86:87], v[86:87], v[124:125]
	v_pk_fma_f32 v[60:61], v[114:115], v[26:27], v[60:61]
	v_pk_mul_f32 v[56:57], v[56:57], v[86:87]
	v_pk_mul_f32 v[86:87], v[120:121], v[122:123]
	v_cvt_pk_bf16_f32 v56, v56, v57
	v_pk_fma_f32 v[60:61], v[82:83], v[30:31], v[60:61]
	v_pk_mul_f32 v[70:71], v[70:71], v[86:87]
	v_pk_mul_f32 v[86:87], v[60:61], v[60:61]
	v_cvt_pk_bf16_f32 v57, v70, v71
	global_store_dwordx2 v[174:175], v[56:57], off offset:8
	v_pk_fma_f32 v[56:57], v[24:25], v[88:89], v[44:45]
	v_pk_fma_f32 v[70:71], v[20:21], v[72:73], v[36:37]
	v_pk_fma_f32 v[56:57], v[116:117], v[28:29], v[56:57]
	v_pk_fma_f32 v[86:87], v[86:87], s[44:45], v[172:173] op_sel_hi:[1,0,0] neg_lo:[1,0,0] neg_hi:[1,0,0]
	v_pk_fma_f32 v[56:57], v[84:85], v[32:33], v[56:57]
	v_pk_mul_f32 v[86:87], v[60:61], v[86:87]
	v_pk_mul_f32 v[72:73], v[56:57], v[56:57]
	v_exp_f32_e32 v86, v86
	v_pk_fma_f32 v[72:73], v[72:73], s[44:45], v[172:173] op_sel_hi:[1,0,0] neg_lo:[1,0,0] neg_hi:[1,0,0]
	v_exp_f32_e32 v87, v87
	v_pk_mul_f32 v[72:73], v[56:57], v[72:73]
	v_pk_fma_f32 v[58:59], v[18:19], v[58:59], v[34:35]
	v_exp_f32_e32 v72, v72
	v_exp_f32_e32 v73, v73
	v_pk_add_f32 v[86:87], v[86:87], 1.0 op_sel_hi:[1,0]
	v_pk_fma_f32 v[58:59], v[94:95], v[14:15], v[58:59]
	v_rcp_f32_e32 v86, v86
	v_rcp_f32_e32 v87, v87
	v_pk_add_f32 v[72:73], v[72:73], 1.0 op_sel_hi:[1,0]
	v_pk_fma_f32 v[70:71], v[96:97], v[16:17], v[70:71]
	v_rcp_f32_e32 v72, v72
	v_rcp_f32_e32 v73, v73
	v_pk_fma_f32 v[58:59], v[74:75], v[10:11], v[58:59]
	v_pk_mul_f32 v[60:61], v[60:61], v[86:87]
	v_pk_fma_f32 v[70:71], v[76:77], v[12:13], v[70:71]
	v_pk_mul_f32 v[58:59], v[58:59], v[60:61]
	v_pk_mul_f32 v[56:57], v[56:57], v[72:73]
	v_cvt_pk_bf16_f32 v58, v58, v59
	v_pk_fma_f32 v[60:61], v[96:97], v[20:21], v[36:37]
	v_pk_mul_f32 v[56:57], v[70:71], v[56:57]
	v_pk_fma_f32 v[70:71], v[94:95], v[18:19], v[34:35]
	v_cvt_pk_bf16_f32 v59, v56, v57
	global_store_dwordx2 v[176:177], v[58:59], off offset:8
	v_pk_fma_f32 v[58:59], v[114:115], v[22:23], v[42:43]
	v_pk_fma_f32 v[56:57], v[116:117], v[24:25], v[44:45]
	v_pk_fma_f32 v[58:59], v[82:83], v[26:27], v[58:59]
	v_pk_fma_f32 v[56:57], v[84:85], v[28:29], v[56:57]
	v_pk_fma_f32 v[58:59], v[90:91], v[30:31], v[58:59]
	v_pk_fma_f32 v[56:57], v[92:93], v[32:33], v[56:57]
	v_pk_mul_f32 v[86:87], v[58:59], v[58:59]
	v_pk_mul_f32 v[72:73], v[56:57], v[56:57]
	v_pk_fma_f32 v[86:87], v[86:87], s[44:45], v[172:173] op_sel_hi:[1,0,0] neg_lo:[1,0,0] neg_hi:[1,0,0]
	v_pk_fma_f32 v[72:73], v[72:73], s[44:45], v[172:173] op_sel_hi:[1,0,0] neg_lo:[1,0,0] neg_hi:[1,0,0]
	v_pk_mul_f32 v[86:87], v[58:59], v[86:87]
	v_pk_mul_f32 v[72:73], v[56:57], v[72:73]
	v_exp_f32_e32 v86, v86
	v_exp_f32_e32 v87, v87
	v_exp_f32_e32 v72, v72
	v_exp_f32_e32 v73, v73
	v_pk_fma_f32 v[70:71], v[74:75], v[14:15], v[70:71]
	v_pk_add_f32 v[86:87], v[86:87], 1.0 op_sel_hi:[1,0]
	v_pk_fma_f32 v[60:61], v[76:77], v[16:17], v[60:61]
	v_rcp_f32_e32 v86, v86
	v_rcp_f32_e32 v87, v87
	v_pk_add_f32 v[72:73], v[72:73], 1.0 op_sel_hi:[1,0]
; #define PG8_LAS __attribute__((address_space(3)))
;     __device__ __forceinline__ void operator()(f32x4 (&acc)[2][2][4][2], const Unit& u, const Unit& nxt, bool has_next, int ui, int wr, int wc, int fr, int fq) const {
;     ...
; #pragma unroll
;             for (int m = 0; m < 4; ++m)
; #pragma unroll
;                 for (int bj = 0; bj < 2; ++bj) { acc[ai][bj][m][0] *= q[m]; acc[ai][bj][m][1] *= q[m]; } }
;     ...
;             for (int ai = 0; ai < 2; ++ai) { const int blk = 2 * ai + wr; const int pblk = blk > 0 ? blk - 1 : 0; const float hz = blk > 0 ? 1.0f : 0.0f;
;                 f32x4 q2[2], q3[2];
; #pragma unroll
;                 for (int bj = 0; bj < 2; ++bj) {
;                     const PG8_LAS f32x4* hp = (const PG8_LAS f32x4*)(halo + ((pblk * 4 + wc) * 4 + fq) * 32 + (bj * 8 + n * 4) * 2);
;                     const f32x4 ha = hp[0] * hz, hb = hp[1] * hz;
;                     q2[bj][0] = dpp_shr1(ha[0], acc[ai][bj][2][n][0]); q3[bj][0] = dpp_shr1(ha[1], acc[ai][bj][3][n][0]);
;                     q2[bj][1] = dpp_shr1(ha[2], acc[ai][bj][2][n][1]); q3[bj][1] = dpp_shr1(ha[3], acc[ai][bj][3][n][1]);
;                     q2[bj][2] = dpp_shr1(hb[0], acc[ai][bj][2][n][2]); q3[bj][2] = dpp_shr1(hb[1], acc[ai][bj][3][n][2]);
;                     q2[bj][3] = dpp_shr1(hb[2], acc[ai][bj][2][n][3]); q3[bj][3] = dpp_shr1(hb[3], acc[ai][bj][3][n][3]); }
; #pragma unroll
;                 for (int m = 0; m < 4; ++m) { const int row = row0 + ai * HALF + m;
;                     const f32x4 s1g = (m == 0) ? q3[0] : acc[ai][0][m > 0 ? m - 1 : 0][n], s2g = (m == 0) ? q2[0] : (m == 1) ? q3[0] : acc[ai][0][m > 1 ? m - 2 : 0][n];
;                     const f32x4 s1v = (m == 0) ? q3[1] : acc[ai][1][m > 0 ? m - 1 : 0][n], s2v = (m == 0) ? q2[1] : (m == 1) ? q3[1] : acc[ai][1][m > 1 ? m - 2 : 0][n];
;                     const f32x4 cgt = bg + wg[0] * s2g + wg[1] * s1g + wg[2] * acc[ai][0][m][n], cvl = bv + wv[0] * s2v + wv[1] * s1v + wv[2] * acc[ai][1][m][n];
;                     const f32x2p o01 = gelu_tanh_pk((f32x2p){cgt[0], cgt[1]}) * (f32x2p){cvl[0], cvl[1]}, o23 = gelu_tanh_pk((f32x2p){cgt[2], cgt[3]}) * (f32x2p){cvl[2], cvl[3]};
;                     u32x2 w; w.x = cvt_pk_bf16(o01.x, o01.y); w.y = cvt_pk_bf16(o23.x, o23.y);
;                     *(u32x2*)(G + (size_t)row * 12288 + cbase + 4 * n) = w; } } }
	v_pk_fma_f32 v[70:71], v[98:99], v[10:11], v[70:71]
	v_rcp_f32_e32 v72, v72
	v_rcp_f32_e32 v73, v73
	v_pk_mul_f32 v[58:59], v[58:59], v[86:87]
	v_pk_fma_f32 v[60:61], v[100:101], v[12:13], v[60:61]
	v_pk_mul_f32 v[58:59], v[70:71], v[58:59]
	v_pk_mul_f32 v[56:57], v[56:57], v[72:73]
	v_cvt_pk_bf16_f32 v58, v58, v59
	v_pk_fma_f32 v[70:71], v[74:75], v[18:19], v[34:35]
	v_pk_mul_f32 v[56:57], v[60:61], v[56:57]
	v_pk_fma_f32 v[60:61], v[76:77], v[20:21], v[36:37]
	v_cvt_pk_bf16_f32 v59, v56, v57
	global_store_dwordx2 v[118:119], v[58:59], off offset:8
	v_pk_fma_f32 v[56:57], v[84:85], v[24:25], v[44:45]
	v_pk_fma_f32 v[58:59], v[82:83], v[22:23], v[42:43]
	v_pk_fma_f32 v[56:57], v[92:93], v[28:29], v[56:57]
	v_pk_fma_f32 v[58:59], v[90:91], v[26:27], v[58:59]
	v_pk_fma_f32 v[56:57], v[112:113], v[32:33], v[56:57]
	v_pk_fma_f32 v[58:59], v[110:111], v[30:31], v[58:59]
	v_pk_mul_f32 v[72:73], v[56:57], v[56:57]
	v_pk_mul_f32 v[74:75], v[58:59], v[58:59]
	v_pk_fma_f32 v[72:73], v[72:73], s[44:45], v[172:173] op_sel_hi:[1,0,0] neg_lo:[1,0,0] neg_hi:[1,0,0]
	v_pk_fma_f32 v[74:75], v[74:75], s[44:45], v[172:173] op_sel_hi:[1,0,0] neg_lo:[1,0,0] neg_hi:[1,0,0]
	v_pk_mul_f32 v[72:73], v[56:57], v[72:73]
	v_pk_mul_f32 v[74:75], v[58:59], v[74:75]
	v_exp_f32_e32 v72, v72
	v_exp_f32_e32 v74, v74
	v_exp_f32_e32 v75, v75
	v_exp_f32_e32 v73, v73
	v_pk_fma_f32 v[60:61], v[100:101], v[16:17], v[60:61]
	v_pk_fma_f32 v[70:71], v[98:99], v[14:15], v[70:71]
	v_pk_add_f32 v[74:75], v[74:75], 1.0 op_sel_hi:[1,0]
	v_pk_add_f32 v[72:73], v[72:73], 1.0 op_sel_hi:[1,0]
	v_rcp_f32_e32 v74, v74
	v_rcp_f32_e32 v75, v75
	v_rcp_f32_e32 v72, v72
	v_rcp_f32_e32 v73, v73
	v_pk_fma_f32 v[60:61], v[104:105], v[12:13], v[60:61]
	v_pk_fma_f32 v[70:71], v[102:103], v[10:11], v[70:71]
	v_pk_mul_f32 v[58:59], v[58:59], v[74:75]
	v_pk_mul_f32 v[56:57], v[56:57], v[72:73]
	v_pk_mul_f32 v[58:59], v[70:71], v[58:59]
	v_pk_mul_f32 v[56:57], v[60:61], v[56:57]
	v_cvt_pk_bf16_f32 v60, v58, v59
	v_pk_mul_f32 v[2:3], v[2:3], v[62:63] op_sel:[0,1]
	v_cvt_pk_bf16_f32 v61, v56, v57
	ds_read_b128 v[56:59], v214
	ds_read_b128 v[70:73], v215
	v_pk_mul_f32 v[4:5], v[4:5], v[62:63] op_sel:[0,1]
	global_store_dwordx2 v[78:79], v[60:61], off offset:8
	ds_read_b128 v[60:63], v217
	s_waitcnt lgkmcnt(0)
	v_pk_mul_f32 v[74:75], v[150:151], v[58:59]
	v_pk_mul_f32 v[76:77], v[152:153], v[56:57]
	ds_read_b128 v[56:59], v216
	v_pk_mul_f32 v[72:73], v[150:151], v[72:73]
	v_pk_mul_f32 v[70:71], v[152:153], v[70:71]
	v_mov_b32_dpp v76, v66 row_shr:1 row_mask:0xf bank_mask:0xf
	v_mov_b32_dpp v74, v67 row_shr:1 row_mask:0xf bank_mask:0xf
	v_mov_b32_dpp v77, v50 row_shr:1 row_mask:0xf bank_mask:0xf
	v_mov_b32_dpp v70, v68 row_shr:1 row_mask:0xf bank_mask:0xf
	v_mov_b32_dpp v72, v69 row_shr:1 row_mask:0xf bank_mask:0xf
	s_waitcnt lgkmcnt(0)
	v_pk_mul_f32 v[58:59], v[150:151], v[58:59]
	v_pk_mul_f32 v[56:57], v[152:153], v[56:57]
	v_mov_b32_e32 v82, v76
	v_mov_b32_e32 v83, v74
	v_mov_b32_dpp v75, v51 row_shr:1 row_mask:0xf bank_mask:0xf
	v_mov_b32_dpp v71, v52 row_shr:1 row_mask:0xf bank_mask:0xf
	v_pk_mul_f32 v[62:63], v[150:151], v[62:63]
	v_pk_mul_f32 v[60:61], v[152:153], v[60:61]
	v_mov_b32_dpp v56, v46 row_shr:1 row_mask:0xf bank_mask:0xf
	v_mov_b32_dpp v58, v47 row_shr:1 row_mask:0xf bank_mask:0xf
	v_mov_b32_e32 v78, v70
	v_mov_b32_e32 v79, v72
	v_pk_fma_f32 v[82:83], v[22:23], v[82:83], v[42:43]
	v_mov_b32_e32 v74, v77
	v_mov_b32_dpp v73, v53 row_shr:1 row_mask:0xf bank_mask:0xf
	v_mov_b32_dpp v57, v38 row_shr:1 row_mask:0xf bank_mask:0xf
	v_mov_b32_dpp v60, v48 row_shr:1 row_mask:0xf bank_mask:0xf
	v_mov_b32_dpp v62, v49 row_shr:1 row_mask:0xf bank_mask:0xf
	v_pk_fma_f32 v[78:79], v[24:25], v[78:79], v[44:45]
	v_mov_b32_e32 v72, v71
	v_pk_fma_f32 v[76:77], v[26:27], v[74:75], v[82:83]
	v_mov_b32_e32 v82, v56
	v_mov_b32_e32 v83, v58
	v_mov_b32_dpp v59, v39 row_shr:1 row_mask:0xf bank_mask:0xf
	v_mov_b32_dpp v61, v40 row_shr:1 row_mask:0xf bank_mask:0xf
	v_pk_fma_f32 v[70:71], v[28:29], v[72:73], v[78:79]
	v_pk_fma_f32 v[76:77], v[166:167], v[30:31], v[76:77]
	v_mov_b32_e32 v78, v60
	v_mov_b32_e32 v79, v62
	v_pk_fma_f32 v[82:83], v[18:19], v[82:83], v[34:35]
	v_mov_b32_e32 v58, v57
	v_mov_b32_dpp v63, v41 row_shr:1 row_mask:0xf bank_mask:0xf
	v_pk_fma_f32 v[70:71], v[168:169], v[32:33], v[70:71]
	v_pk_fma_f32 v[78:79], v[20:21], v[78:79], v[36:37]
	v_mov_b32_e32 v62, v61
	v_pk_fma_f32 v[56:57], v[14:15], v[58:59], v[82:83]
	v_pk_mul_f32 v[82:83], v[76:77], v[76:77]
	v_pk_fma_f32 v[60:61], v[16:17], v[62:63], v[78:79]
	v_pk_mul_f32 v[78:79], v[70:71], v[70:71]
	v_pk_fma_f32 v[82:83], v[82:83], s[44:45], v[172:173] op_sel_hi:[1,0,0] neg_lo:[1,0,0] neg_hi:[1,0,0]
	v_pk_fma_f32 v[78:79], v[78:79], s[44:45], v[172:173] op_sel_hi:[1,0,0] neg_lo:[1,0,0] neg_hi:[1,0,0]
	v_pk_mul_f32 v[82:83], v[76:77], v[82:83]
	v_pk_mul_f32 v[78:79], v[70:71], v[78:79]
	v_exp_f32_e32 v82, v82
	v_exp_f32_e32 v83, v83
	v_exp_f32_e32 v78, v78
	v_exp_f32_e32 v79, v79
	v_pk_fma_f32 v[56:57], v[144:145], v[10:11], v[56:57]
	v_pk_add_f32 v[82:83], v[82:83], 1.0 op_sel_hi:[1,0]
	v_pk_fma_f32 v[60:61], v[170:171], v[12:13], v[60:61]
	v_rcp_f32_e32 v82, v82
	v_rcp_f32_e32 v83, v83
	v_pk_add_f32 v[78:79], v[78:79], 1.0 op_sel_hi:[1,0]
	v_pk_fma_f32 v[62:63], v[20:21], v[62:63], v[36:37]
; #define PG8_LAS __attribute__((address_space(3)))
; __device__ __forceinline__ unsigned cvt_pk_bf16(float lo, float hi) { unsigned r; asm volatile("v_cvt_pk_bf16_f32 %0, %1, %2" : "=v"(r) : "v"(lo), "v"(hi)); return r; }
; __device__ __forceinline__ f32x2p gelu_tanh_pk(f32x2p v) { const f32x2p t = v * (v * v * -0.10294324f + -2.3022082f); return v * rcp1p_exp2_pk(t); }
;     __device__ __forceinline__ void operator()(f32x4 (&acc)[2][2][4][2], const Unit& u, const Unit& nxt, bool has_next, int ui, int wr, int wc, int fr, int fq) const {
;     ...
; #pragma unroll
;                 for (int m = 0; m < 4; ++m) { const int row = row0 + ai * HALF + m;
;                     const f32x4 s1g = (m == 0) ? q3[0] : acc[ai][0][m > 0 ? m - 1 : 0][n], s2g = (m == 0) ? q2[0] : (m == 1) ? q3[0] : acc[ai][0][m > 1 ? m - 2 : 0][n];
;                     const f32x4 s1v = (m == 0) ? q3[1] : acc[ai][1][m > 0 ? m - 1 : 0][n], s2v = (m == 0) ? q2[1] : (m == 1) ? q3[1] : acc[ai][1][m > 1 ? m - 2 : 0][n];
;                     const f32x4 cgt = bg + wg[0] * s2g + wg[1] * s1g + wg[2] * acc[ai][0][m][n], cvl = bv + wv[0] * s2v + wv[1] * s1v + wv[2] * acc[ai][1][m][n];
;                     const f32x2p o01 = gelu_tanh_pk((f32x2p){cgt[0], cgt[1]}) * (f32x2p){cvl[0], cvl[1]}, o23 = gelu_tanh_pk((f32x2p){cgt[2], cgt[3]}) * (f32x2p){cvl[2], cvl[3]};
;                     u32x2 w; w.x = cvt_pk_bf16(o01.x, o01.y); w.y = cvt_pk_bf16(o23.x, o23.y);
;                     *(u32x2*)(G + (size_t)row * 12288 + cbase + 4 * n) = w; } } }
;         if (ld) *(PG8_LAS f32x4*)(ctab + ((ui + 1) & 1) * 1024 + (tid_ >> 5) * 128 + (tid_ & 31) * 4) = nx;
	v_rcp_f32_e32 v78, v78
	v_rcp_f32_e32 v79, v79
	v_pk_mul_f32 v[76:77], v[76:77], v[82:83]
	v_pk_fma_f32 v[58:59], v[18:19], v[58:59], v[34:35]
	v_pk_mul_f32 v[56:57], v[56:57], v[76:77]
	v_pk_mul_f32 v[70:71], v[70:71], v[78:79]
	v_cvt_pk_bf16_f32 v56, v56, v57
	v_pk_fma_f32 v[62:63], v[170:171], v[16:17], v[62:63]
	v_pk_mul_f32 v[60:61], v[60:61], v[70:71]
	v_pk_fma_f32 v[58:59], v[144:145], v[14:15], v[58:59]
	v_cvt_pk_bf16_f32 v57, v60, v61
	global_store_dwordx2 v[80:81], v[56:57], off offset:8
	v_pk_fma_f32 v[56:57], v[24:25], v[72:73], v[44:45]
	v_pk_fma_f32 v[60:61], v[22:23], v[74:75], v[42:43]
	v_pk_fma_f32 v[56:57], v[168:169], v[28:29], v[56:57]
	v_pk_fma_f32 v[60:61], v[166:167], v[26:27], v[60:61]
	v_pk_fma_f32 v[56:57], v[142:143], v[32:33], v[56:57]
	v_pk_fma_f32 v[60:61], v[64:65], v[30:31], v[60:61]
	v_pk_mul_f32 v[70:71], v[56:57], v[56:57]
	v_pk_mul_f32 v[72:73], v[60:61], v[60:61]
	v_pk_fma_f32 v[70:71], v[70:71], s[44:45], v[172:173] op_sel_hi:[1,0,0] neg_lo:[1,0,0] neg_hi:[1,0,0]
	v_pk_fma_f32 v[72:73], v[72:73], s[44:45], v[172:173] op_sel_hi:[1,0,0] neg_lo:[1,0,0] neg_hi:[1,0,0]
	v_pk_mul_f32 v[70:71], v[56:57], v[70:71]
	v_pk_mul_f32 v[72:73], v[60:61], v[72:73]
	v_exp_f32_e32 v70, v70
	v_exp_f32_e32 v72, v72
	v_exp_f32_e32 v73, v73
	v_exp_f32_e32 v71, v71
	v_pk_fma_f32 v[62:63], v[4:5], v[12:13], v[62:63]
	v_pk_fma_f32 v[58:59], v[2:3], v[10:11], v[58:59]
	v_pk_add_f32 v[72:73], v[72:73], 1.0 op_sel_hi:[1,0]
	v_pk_add_f32 v[70:71], v[70:71], 1.0 op_sel_hi:[1,0]
	v_rcp_f32_e32 v72, v72
	v_rcp_f32_e32 v73, v73
	v_rcp_f32_e32 v70, v70
	v_rcp_f32_e32 v71, v71
	v_pk_mul_f32 v[60:61], v[60:61], v[72:73]
	s_nop 0
	v_pk_mul_f32 v[58:59], v[58:59], v[60:61]
	v_pk_mul_f32 v[56:57], v[56:57], v[70:71]
	v_cvt_pk_bf16_f32 v58, v58, v59
	v_pk_fma_f32 v[60:61], v[170:171], v[20:21], v[36:37]
	v_pk_mul_f32 v[56:57], v[62:63], v[56:57]
	v_pk_fma_f32 v[62:63], v[144:145], v[18:19], v[34:35]
	v_cvt_pk_bf16_f32 v59, v56, v57
	v_pk_fma_f32 v[56:57], v[166:167], v[22:23], v[42:43]
	v_pk_fma_f32 v[22:23], v[64:65], v[22:23], v[42:43]
	global_store_dwordx2 v[106:107], v[58:59], off offset:8
	v_pk_fma_f32 v[58:59], v[168:169], v[24:25], v[44:45]
	v_pk_fma_f32 v[56:57], v[64:65], v[26:27], v[56:57]
	v_pk_fma_f32 v[24:25], v[142:143], v[24:25], v[44:45]
	v_pk_fma_f32 v[22:23], v[66:67], v[26:27], v[22:23]
	v_pk_fma_f32 v[58:59], v[142:143], v[28:29], v[58:59]
	v_pk_fma_f32 v[56:57], v[66:67], v[30:31], v[56:57]
	v_pk_fma_f32 v[62:63], v[2:3], v[14:15], v[62:63]
	v_pk_fma_f32 v[60:61], v[4:5], v[16:17], v[60:61]
	v_pk_fma_f32 v[24:25], v[68:69], v[28:29], v[24:25]
	v_pk_fma_f32 v[22:23], v[50:51], v[30:31], v[22:23]
	v_pk_fma_f32 v[4:5], v[4:5], v[20:21], v[36:37]
	v_pk_fma_f32 v[2:3], v[2:3], v[18:19], v[34:35]
	v_pk_fma_f32 v[58:59], v[68:69], v[32:33], v[58:59]
	v_pk_mul_f32 v[72:73], v[56:57], v[56:57]
	v_pk_fma_f32 v[24:25], v[52:53], v[32:33], v[24:25]
	v_pk_fma_f32 v[2:3], v[46:47], v[14:15], v[2:3]
	v_pk_fma_f32 v[4:5], v[48:49], v[16:17], v[4:5]
	v_pk_mul_f32 v[14:15], v[22:23], v[22:23]
	v_pk_fma_f32 v[60:61], v[48:49], v[12:13], v[60:61]
	v_pk_mul_f32 v[70:71], v[58:59], v[58:59]
	v_pk_fma_f32 v[72:73], v[72:73], s[44:45], v[172:173] op_sel_hi:[1,0,0] neg_lo:[1,0,0] neg_hi:[1,0,0]
	v_pk_fma_f32 v[4:5], v[40:41], v[12:13], v[4:5]
	v_pk_mul_f32 v[12:13], v[24:25], v[24:25]
	v_pk_fma_f32 v[14:15], v[14:15], s[44:45], v[172:173] op_sel_hi:[1,0,0] neg_lo:[1,0,0] neg_hi:[1,0,0]
	v_pk_mul_f32 v[72:73], v[56:57], v[72:73]
	v_pk_fma_f32 v[70:71], v[70:71], s[44:45], v[172:173] op_sel_hi:[1,0,0] neg_lo:[1,0,0] neg_hi:[1,0,0]
	v_pk_mul_f32 v[14:15], v[22:23], v[14:15]
	v_pk_fma_f32 v[12:13], v[12:13], s[44:45], v[172:173] op_sel_hi:[1,0,0] neg_lo:[1,0,0] neg_hi:[1,0,0]
	v_exp_f32_e32 v72, v72
	v_exp_f32_e32 v73, v73
	v_pk_mul_f32 v[70:71], v[58:59], v[70:71]
	v_exp_f32_e32 v14, v14
	v_exp_f32_e32 v15, v15
	v_pk_mul_f32 v[12:13], v[24:25], v[12:13]
	v_exp_f32_e32 v70, v70
	v_exp_f32_e32 v71, v71
	v_exp_f32_e32 v12, v12
	v_exp_f32_e32 v13, v13
	v_pk_add_f32 v[72:73], v[72:73], 1.0 op_sel_hi:[1,0]
	v_pk_add_f32 v[14:15], v[14:15], 1.0 op_sel_hi:[1,0]
	v_rcp_f32_e32 v72, v72
	v_rcp_f32_e32 v73, v73
	v_pk_add_f32 v[70:71], v[70:71], 1.0 op_sel_hi:[1,0]
	v_rcp_f32_e32 v14, v14
	v_rcp_f32_e32 v15, v15
	v_pk_add_f32 v[12:13], v[12:13], 1.0 op_sel_hi:[1,0]
	v_rcp_f32_e32 v70, v70
	v_rcp_f32_e32 v71, v71
	v_rcp_f32_e32 v12, v12
	v_rcp_f32_e32 v13, v13
	v_pk_fma_f32 v[62:63], v[46:47], v[10:11], v[62:63]
	v_pk_mul_f32 v[56:57], v[56:57], v[72:73]
	v_pk_fma_f32 v[2:3], v[38:39], v[10:11], v[2:3]
	v_pk_mul_f32 v[10:11], v[22:23], v[14:15]
	v_pk_mul_f32 v[56:57], v[62:63], v[56:57]
	v_pk_mul_f32 v[58:59], v[58:59], v[70:71]
	v_pk_mul_f32 v[2:3], v[2:3], v[10:11]
	v_pk_mul_f32 v[10:11], v[24:25], v[12:13]
	v_pk_mul_f32 v[58:59], v[60:61], v[58:59]
	v_cvt_pk_bf16_f32 v56, v56, v57
	v_pk_mul_f32 v[4:5], v[4:5], v[10:11]
	v_cvt_pk_bf16_f32 v57, v58, v59
	global_store_dwordx2 v[108:109], v[56:57], off offset:8
	v_cvt_pk_bf16_f32 v2, v2, v3
	v_cvt_pk_bf16_f32 v3, v4, v5
	global_store_dwordx2 v[54:55], v[2:3], off offset:8
	s_and_saveexec_b64 s[2:3], s[62:63]
	s_cbranch_execz .LBB0_986
	s_xor_b32 s12, s12, 0x400
	v_lshl_add_u32 v2, s12, 2, v207
	s_waitcnt vmcnt(16)
	ds_write_b128 v2, v[6:9]
